# v16 + grid-barrier aggregation loop de-serialised: 16 counter loads issued back to back, one wait, then summed
# speedup vs baseline: 1.0042x; 1.0042x over previous
.LBB0_330:
	v_readlane_b32 s4, v254, 11
	v_readlane_b32 s5, v254, 12
	s_mov_b64 s[22:23], -1
	s_nop 3
	global_load_dword v1, v191, s[4:5] sc1
	v_readlane_b32 s4, v254, 13
	v_readlane_b32 s5, v254, 14
	s_nop 4
	global_load_dword v2, v191, s[4:5] sc1
	v_readlane_b32 s4, v254, 15
	v_readlane_b32 s5, v254, 16
	s_nop 4
	global_load_dword v3, v191, s[4:5] sc1
	v_readlane_b32 s4, v254, 17
	v_readlane_b32 s5, v254, 18
	s_nop 4
	global_load_dword v4, v191, s[4:5] sc1
	v_readlane_b32 s4, v254, 19
	v_readlane_b32 s5, v254, 20
	s_nop 4
	global_load_dword v5, v191, s[4:5] sc1
	v_readlane_b32 s4, v254, 21
	v_readlane_b32 s5, v254, 22
	s_nop 4
	global_load_dword v6, v191, s[4:5] sc1
	v_readlane_b32 s4, v254, 23
	v_readlane_b32 s5, v254, 24
	s_nop 4
	global_load_dword v7, v191, s[4:5] sc1
	v_readlane_b32 s4, v254, 25
	v_readlane_b32 s5, v254, 26
	s_nop 4
	global_load_dword v8, v191, s[4:5] sc1
	v_readlane_b32 s4, v254, 27
	v_readlane_b32 s5, v254, 28
	s_nop 4
	global_load_dword v9, v191, s[4:5] sc1
	v_readlane_b32 s4, v254, 29
	v_readlane_b32 s5, v254, 30
	s_nop 4
	global_load_dword v10, v191, s[4:5] sc1
	v_readlane_b32 s4, v254, 31
	v_readlane_b32 s5, v254, 32
	s_nop 4
	global_load_dword v11, v191, s[4:5] sc1
	v_readlane_b32 s4, v254, 33
	v_readlane_b32 s5, v254, 34
	s_nop 4
	global_load_dword v12, v191, s[4:5] sc1
	v_readlane_b32 s4, v254, 35
	v_readlane_b32 s5, v254, 36
	s_nop 4
	global_load_dword v13, v191, s[4:5] sc1
	v_readlane_b32 s4, v254, 37
	v_readlane_b32 s5, v254, 38
	s_nop 4
	global_load_dword v14, v191, s[4:5] sc1
	v_readlane_b32 s4, v254, 39
	v_readlane_b32 s5, v254, 40
	s_nop 4
	global_load_dword v15, v191, s[4:5] sc1
	v_readlane_b32 s4, v254, 41
	v_readlane_b32 s5, v254, 42
	s_nop 4
	global_load_dword v16, v191, s[4:5] sc1
	s_mov_b64 s[4:5], -1
	s_waitcnt vmcnt(0)
	v_add_u32_e32 v17, v2, v1
	v_add_u32_e32 v17, v17, v3
	v_add_u32_e32 v17, v17, v4
	v_add_u32_e32 v17, v17, v5
	v_add_u32_e32 v17, v17, v6
	v_add_u32_e32 v17, v17, v7
	v_add_u32_e32 v17, v17, v8
	v_add_u32_e32 v17, v17, v9
	v_add_u32_e32 v17, v17, v10
	v_add_u32_e32 v17, v17, v11
	v_add_u32_e32 v17, v17, v12
	v_add_u32_e32 v17, v17, v13
	v_add_u32_e32 v17, v17, v14
	v_add_u32_e32 v17, v17, v15
	v_add_u32_e32 v17, v17, v16
	v_cmp_eq_u32_e32 vcc, s10, v17
	s_cbranch_vccnz .LBB0_329
	s_and_b32 s4, s11, 0xff
	s_cmp_eq_u32 s4, 0
	s_mov_b64 s[4:5], -1
	s_mov_b64 s[30:31], -1
	s_sleep 1
	s_cbranch_scc0 .LBB0_334
	global_load_dword v17, v191, s[56:57] sc1
	s_waitcnt vmcnt(0)
	v_cmp_eq_u32_e32 vcc, 0, v17
	s_cbranch_vccnz .LBB0_336
	s_mov_b64 s[30:31], 0

.LBB0_1106:
	v_readlane_b32 s4, v254, 11
	v_readlane_b32 s5, v254, 12
	s_mov_b64 s[22:23], -1
	s_nop 3
	global_load_dword v1, v191, s[4:5] sc1
	v_readlane_b32 s4, v254, 13
	v_readlane_b32 s5, v254, 14
	s_nop 4
	global_load_dword v2, v191, s[4:5] sc1
	v_readlane_b32 s4, v254, 15
	v_readlane_b32 s5, v254, 16
	s_nop 4
	global_load_dword v3, v191, s[4:5] sc1
	v_readlane_b32 s4, v254, 17
	v_readlane_b32 s5, v254, 18
	s_nop 4
	global_load_dword v4, v191, s[4:5] sc1
	v_readlane_b32 s4, v254, 19
	v_readlane_b32 s5, v254, 20
	s_nop 4
	global_load_dword v5, v191, s[4:5] sc1
	v_readlane_b32 s4, v254, 21
	v_readlane_b32 s5, v254, 22
	s_nop 4
	global_load_dword v6, v191, s[4:5] sc1
	v_readlane_b32 s4, v254, 23
	v_readlane_b32 s5, v254, 24
	s_nop 4
	global_load_dword v7, v191, s[4:5] sc1
	v_readlane_b32 s4, v254, 25
	v_readlane_b32 s5, v254, 26
	s_nop 4
	global_load_dword v8, v191, s[4:5] sc1
	v_readlane_b32 s4, v254, 27
	v_readlane_b32 s5, v254, 28
	s_nop 4
	global_load_dword v9, v191, s[4:5] sc1
	v_readlane_b32 s4, v254, 29
	v_readlane_b32 s5, v254, 30
	s_nop 4
	global_load_dword v10, v191, s[4:5] sc1
	v_readlane_b32 s4, v254, 31
	v_readlane_b32 s5, v254, 32
	s_nop 4
	global_load_dword v11, v191, s[4:5] sc1
	v_readlane_b32 s4, v254, 33
	v_readlane_b32 s5, v254, 34
	s_nop 4
	global_load_dword v12, v191, s[4:5] sc1
	v_readlane_b32 s4, v254, 35
	v_readlane_b32 s5, v254, 36
	s_nop 4
	global_load_dword v13, v191, s[4:5] sc1
	v_readlane_b32 s4, v254, 37
	v_readlane_b32 s5, v254, 38
	s_nop 4
	global_load_dword v14, v191, s[4:5] sc1
	v_readlane_b32 s4, v254, 39
	v_readlane_b32 s5, v254, 40
	s_nop 4
	global_load_dword v15, v191, s[4:5] sc1
	v_readlane_b32 s4, v254, 41
	v_readlane_b32 s5, v254, 42
	s_nop 4
	global_load_dword v16, v191, s[4:5] sc1
	s_mov_b64 s[4:5], -1
	s_waitcnt vmcnt(0)
	v_add_u32_e32 v17, v2, v1
	v_add_u32_e32 v17, v17, v3
	v_add_u32_e32 v17, v17, v4
	v_add_u32_e32 v17, v17, v5
	v_add_u32_e32 v17, v17, v6
	v_add_u32_e32 v17, v17, v7
	v_add_u32_e32 v17, v17, v8
	v_add_u32_e32 v17, v17, v9
	v_add_u32_e32 v17, v17, v10
	v_add_u32_e32 v17, v17, v11
	v_add_u32_e32 v17, v17, v12
	v_add_u32_e32 v17, v17, v13
	v_add_u32_e32 v17, v17, v14
	v_add_u32_e32 v17, v17, v15
	v_add_u32_e32 v17, v17, v16
	v_cmp_eq_u32_e32 vcc, s3, v17
	s_cbranch_vccnz .LBB0_1105
	s_and_b32 s4, s10, 0xff
	s_cmp_eq_u32 s4, 0
	s_mov_b64 s[4:5], -1
	s_mov_b64 s[30:31], -1
	s_sleep 1
	s_cbranch_scc0 .LBB0_1110
	global_load_dword v17, v191, s[56:57] sc1
	s_waitcnt vmcnt(0)
	v_cmp_eq_u32_e32 vcc, 0, v17
	s_cbranch_vccnz .LBB0_1112
	s_mov_b64 s[30:31], 0
